# v37 with non-uniform XCD-class start stagger (0,2,6,12 sleeps instead of 0,4,8,12)
# speedup vs baseline: 1.0009x; 1.0009x over previous
.LBB0_914:
	s_cmp_lt_i32 s24, 5
	s_cselect_b64 s[6:7], -1, 0
	s_and_b64 s[0:1], s[6:7], s[0:1]
	s_andn2_b64 vcc, exec, s[0:1]
	s_cbranch_vccnz .LBB0_943
	s_add_u32 s8, s22, 0x1be4c100
	s_addc_u32 s9, s23, 0
	v_and_b32_e32 v0, 63, v144
	global_load_ubyte v1, v0, s[8:9] sc1
	global_load_ubyte v2, v0, s[8:9] offset:64 sc1
	global_load_ubyte v3, v0, s[8:9] offset:128 sc1
	global_load_ubyte v4, v0, s[8:9] offset:192 sc1
	s_waitcnt vmcnt(0)
	v_cmp_eq_u32_e32 vcc, v1, v2
	v_cmp_eq_u32_e64 s[10:11], v1, v3
	v_cmp_eq_u32_e64 s[12:13], v1, v4
	v_cmp_ne_u32_e64 s[14:15], 0, v1
	s_nop 3
	s_and_b64 s[10:11], s[10:11], s[12:13]
	s_and_b64 s[10:11], s[10:11], s[14:15]
	s_and_b64 vcc, vcc, s[10:11]
	s_cmp_eq_u64 vcc, exec
	s_cselect_b32 s32, 1, 0
	s_cmp_eq_u32 s32, 0
	s_cbranch_scc1 .Lstag_done
	s_and_b32 s98, s3, 3
	s_add_i32 s99, s98, 1
	s_mul_i32 s98, s98, s99
	s_cmp_eq_u32 s98, 0
	s_cbranch_scc1 .Lstag_done
.Lstag_loop:
	s_sleep 127
	s_add_i32 s98, s98, -1
	s_cmp_lg_u32 s98, 0
	s_cbranch_scc1 .Lstag_loop
